# opt47: opt41 with every s_setprio flip deleted in both attention phases (flat priority)
# speedup vs baseline: 1.0105x; 1.0016x over previous
; template <bool SWA>
; __device__ __forceinline__ void unit(LAS unsigned char* lds, const bf16_t* PROJ, const bf16_t* KT, const bf16_t* VT, bf16_t* OB, int opitch, int ocol, int b, int head, int qb, float slope2, float m_init, float lam, const float* subg) {
;     ...
;     const int krow = (r & 0x13) | ((r & 4) << 1) | ((r & 8) >> 1);
;     int offK[4], offV[4];
; #pragma unroll
;     for (int ks = 0; ks < 4; ++ks) {
;         if (SWA) offK[ks] = krow * 128 + (((2 * ks + h) ^ ((krow >> 1) & 7)) << 4);
;         else offK[ks] = krow * 256 + (((c * 8 + 2 * ks + h) ^ (krow & 15)) << 4);
.LBB0_852:
	v_and_b32_e32 v17, 19, v184
	v_lshrrev_b32_e32 v33, 1, v184
	v_and_or_b32 v16, v16, 8, v17
	v_and_b32_e32 v17, 4, v33
	v_or_b32_e32 v18, v16, v17
	v_lshl_or_b32 v20, s4, 3, v32
	v_lshlrev_b32_e32 v19, 8, v18
	v_bitop3_b32 v16, v16, 15, v17 bitop3:0xc8
	v_bitop3_b32 v17, v18, v20, 15 bitop3:0x6c
	v_lshl_add_u32 v199, v17, 4, v19
	v_bitop3_b32 v17, v20, v16, 2 bitop3:0x36
	v_lshl_add_u32 v200, v17, 4, v19
	v_bitop3_b32 v17, v20, v16, 4 bitop3:0x36
	v_bitop3_b32 v16, v20, v16, 6 bitop3:0x36
	v_lshl_add_u32 v201, v17, 4, v19
	v_lshl_add_u32 v202, v16, 4, v19
	s_or_b32 s0, s42, 64
	s_or_b32 s1, s42, 0x7f
	v_add_u32_e32 v195, 0, v199
	v_add_u32_e32 v196, 0, v200
	v_add_u32_e32 v197, 0, v201
	v_add_u32_e32 v198, 0, v202
	s_cmp_ge_u32 s1, s5
	ds_read_b128 v[34:37], v195
	ds_read_b128 v[38:41], v195 offset:8192
	ds_read_b128 v[42:45], v196
	ds_read_b128 v[46:49], v196 offset:8192
	ds_read_b128 v[50:53], v197
	ds_read_b128 v[54:57], v197 offset:8192
	ds_read_b128 v[58:61], v198
	ds_read_b128 v[66:69], v198 offset:8192
	s_cselect_b64 s[86:87], -1, 0
	s_cmp_lt_u32 s1, s5
	s_cselect_b64 s[78:79], -1, 0
	s_cmp_le_u32 s0, s19
	s_cselect_b64 s[88:89], -1, 0
	s_and_b64 s[80:81], s[86:87], s[88:89]

	s_waitcnt lgkmcnt(7)
	v_mfma_f32_32x32x16_bf16 v[16:31], v[34:37], v[140:143], v[0:15]
	s_waitcnt lgkmcnt(6)
	v_mfma_f32_32x32x16_bf16 v[0:15], v[38:41], v[140:143], v[0:15]
	s_waitcnt lgkmcnt(5)
	v_mfma_f32_32x32x16_bf16 v[16:31], v[42:45], v[136:139], v[16:31]
	s_waitcnt lgkmcnt(4)
	v_mfma_f32_32x32x16_bf16 v[0:15], v[46:49], v[136:139], v[0:15]
	s_waitcnt lgkmcnt(3)
	v_mfma_f32_32x32x16_bf16 v[16:31], v[50:53], v[132:135], v[16:31]
	s_waitcnt lgkmcnt(2)
	v_mfma_f32_32x32x16_bf16 v[0:15], v[54:57], v[132:135], v[0:15]
	s_waitcnt lgkmcnt(1)
	v_mfma_f32_32x32x16_bf16 v[16:31], v[58:61], v[128:131], v[16:31]
	s_waitcnt lgkmcnt(0)
	v_mfma_f32_32x32x16_bf16 v[0:15], v[66:69], v[128:131], v[0:15]

	s_and_b64 vcc, exec, s[80:81]
	v_mov_b32_e32 v65, 0
	v_mov_b32_e32 v66, 0
	v_mov_b32_e32 v67, 0
	v_mov_b32_e32 v68, 0
	v_mov_b32_e32 v69, 0
	v_mov_b32_e32 v70, 0
	v_mov_b32_e32 v71, 0
	v_mov_b32_e32 v72, 0
	v_mov_b32_e32 v73, 0
	v_mov_b32_e32 v74, 0
	v_mov_b32_e32 v75, 0
	v_mov_b32_e32 v76, 0
	v_mov_b32_e32 v77, 0
	v_mov_b32_e32 v78, 0
	v_mov_b32_e32 v79, 0
	s_cbranch_vccnz .LBB0_854
	s_and_b64 s[6:7], s[88:89], exec
	s_cselect_b32 s1, 0, 64
	s_and_b64 s[6:7], s[86:87], exec
	s_cselect_b32 s1, s1, 0
	s_add_i32 s1, s1, 0
	s_add_i32 s1, s1, 0x20200
	v_mov_b32_e32 v34, s1
	ds_read_b128 v[64:67], v34
	ds_read_b128 v[68:71], v34 offset:16
	ds_read_b128 v[72:75], v34 offset:32
	ds_read_b128 v[76:79], v34 offset:48
.LBB0_854:
	ds_read_b128 v[34:37], v195 offset:16384
	ds_read_b128 v[38:41], v195 offset:24576
	ds_read_b128 v[42:45], v196 offset:16384
	ds_read_b128 v[46:49], v196 offset:24576
	ds_read_b128 v[50:53], v197 offset:16384
	ds_read_b128 v[54:57], v197 offset:24576
	ds_read_b128 v[58:61], v198 offset:16384
	ds_read_b128 v[96:99], v198 offset:24576
	v_lshlrev_b32_e32 v187, 3, v32
	s_xor_b64 s[6:7], s[84:85], -1
	v_mul_f32_e32 v194, s76, v183

	s_waitcnt lgkmcnt(7)
	v_mfma_f32_32x32x16_bf16 v[80:95], v[34:37], v[140:143], v[64:79]
	s_waitcnt lgkmcnt(6)
	v_mfma_f32_32x32x16_bf16 v[64:79], v[38:41], v[140:143], v[64:79]
	s_waitcnt lgkmcnt(5)
	v_mfma_f32_32x32x16_bf16 v[80:95], v[42:45], v[136:139], v[80:95]
	s_waitcnt lgkmcnt(4)
	v_mfma_f32_32x32x16_bf16 v[64:79], v[46:49], v[136:139], v[64:79]
	s_waitcnt lgkmcnt(3)
	v_mfma_f32_32x32x16_bf16 v[80:95], v[50:53], v[132:135], v[80:95]
	s_waitcnt lgkmcnt(2)
	v_mfma_f32_32x32x16_bf16 v[64:79], v[54:57], v[132:135], v[64:79]
	s_waitcnt lgkmcnt(1)
	v_mfma_f32_32x32x16_bf16 v[80:95], v[58:61], v[128:131], v[80:95]
	s_waitcnt lgkmcnt(0)
	v_mfma_f32_32x32x16_bf16 v[64:79], v[96:99], v[128:131], v[64:79]

	v_or_b32_e32 v34, s42, v187
	v_sub_u32_e32 v34, v188, v34
	v_cvt_f32_i32_e32 v37, v34
	s_andn2_b64 vcc, exec, s[6:7]
	s_mov_b64 s[6:7], -1
	s_cbranch_vccnz .LBB0_860
	s_andn2_b64 vcc, exec, s[82:83]
	s_cbranch_vccnz .LBB0_857
	v_mul_f32_e64 v35, -s76, v37
	v_fma_f32 v36, -s76, v37, v194
	s_mov_b64 s[6:7], 0

; template <bool SWA>
; __device__ __forceinline__ void unit(LAS unsigned char* lds, const bf16_t* PROJ, const bf16_t* KT, const bf16_t* VT, bf16_t* OB, int opitch, int ocol, int b, int head, int qb, float slope2, float m_init, float lam, const float* subg) {
;     ...
; #pragma unroll
;     for (int ks = 0; ks < 4; ++ks) {
;         if (SWA) offK[ks] = krow * 128 + (((2 * ks + h) ^ ((krow >> 1) & 7)) << 4);
;         else offK[ks] = krow * 256 + (((c * 8 + 2 * ks + h) ^ (krow & 15)) << 4);
;         offV[ks] = r * 128 + (((2 * ks + h) ^ ((r >> 1) & 7)) << 4);
;     }
.LBB0_865:
	v_lshlrev_b32_e32 v0, 7, v185
	v_and_b32_e32 v1, 7, v33
	v_bitop3_b32 v2, v32, v33, 7 bitop3:0x78
	v_lshl_or_b32 v189, v2, 4, v0
	v_bitop3_b32 v2, v32, v1, 2 bitop3:0x36
	v_lshl_or_b32 v190, v2, 4, v0
	v_bitop3_b32 v2, v32, v1, 4 bitop3:0x36
	v_bitop3_b32 v1, v32, v1, 6 bitop3:0x36
	v_lshl_or_b32 v191, v2, 4, v0
	s_andn2_b64 vcc, exec, s[82:83]
	v_lshl_or_b32 v192, v1, 4, v0
	s_cbranch_vccnz .LBB0_867
	s_add_i32 s1, 0, 0x10000
	v_add_u32_e32 v4, s1, v189
	v_add_u32_e32 v12, s1, v190
	v_add_u32_e32 v36, s1, v191
	v_add_u32_e32 v44, s1, v192
	ds_read_b128 v[0:3], v4
	ds_read_b128 v[4:7], v4 offset:4096
	ds_read_b128 v[8:11], v12
	ds_read_b128 v[12:15], v12 offset:4096
	ds_read_b128 v[32:35], v36
	ds_read_b128 v[36:39], v36 offset:4096
	ds_read_b128 v[40:43], v44
	ds_read_b128 v[44:47], v44 offset:4096

	s_waitcnt lgkmcnt(6)
	v_mfma_f32_32x32x16_bf16 v[48:63], v[4:7], v[144:147], v[16:31]
	v_mfma_f32_32x32x16_bf16 v[96:111], v[0:3], v[144:147], v[16:31]
	s_waitcnt lgkmcnt(4)
	v_mfma_f32_32x32x16_bf16 v[48:63], v[12:15], v[148:151], v[48:63]
	v_mfma_f32_32x32x16_bf16 v[96:111], v[8:11], v[148:151], v[96:111]
	s_waitcnt lgkmcnt(2)
	v_mfma_f32_32x32x16_bf16 v[48:63], v[36:39], v[152:155], v[48:63]
	v_mfma_f32_32x32x16_bf16 v[96:111], v[32:35], v[152:155], v[96:111]
	s_waitcnt lgkmcnt(0)
	v_mfma_f32_32x32x16_bf16 v[48:63], v[44:47], v[156:159], v[48:63]
	v_mfma_f32_32x32x16_bf16 v[96:111], v[40:43], v[156:159], v[96:111]

	v_readlane_b32 s1, v255, 2
	s_nop 1
	v_add_u32_e32 v4, s1, v189
	v_add_u32_e32 v12, s1, v190
	v_add_u32_e32 v32, s1, v191
	v_add_u32_e32 v33, s1, v192
	ds_read_b128 v[0:3], v4
	ds_read_b128 v[4:7], v4 offset:4096
	ds_read_b128 v[8:11], v12
	ds_read_b128 v[12:15], v12 offset:4096
	ds_read_b128 v[114:117], v32
	ds_read_b128 v[118:121], v32 offset:4096
	ds_read_b128 v[122:125], v33
	ds_read_b128 v[204:207], v33 offset:4096

	s_waitcnt lgkmcnt(7)
	v_mfma_f32_32x32x16_bf16 v[32:47], v[0:3], v[144:147], v[16:31]
	s_waitcnt lgkmcnt(6)
	v_mfma_f32_32x32x16_bf16 v[16:31], v[4:7], v[144:147], v[16:31]
	s_waitcnt lgkmcnt(4)
	v_mfma_f32_32x32x16_bf16 v[16:31], v[12:15], v[148:151], v[16:31]
	v_mfma_f32_32x32x16_bf16 v[32:47], v[8:11], v[148:151], v[32:47]
	s_waitcnt lgkmcnt(2)
	v_mfma_f32_32x32x16_bf16 v[16:31], v[118:121], v[152:155], v[16:31]
	v_mfma_f32_32x32x16_bf16 v[32:47], v[114:117], v[152:155], v[32:47]
	s_nop 10
	v_mov_b64_e32 v[0:1], v[16:17]
	v_mov_b64_e32 v[2:3], v[18:19]
	v_mov_b64_e32 v[4:5], v[20:21]
	v_mov_b64_e32 v[6:7], v[22:23]
	v_mov_b64_e32 v[8:9], v[24:25]
	v_mov_b64_e32 v[10:11], v[26:27]
	v_mov_b64_e32 v[12:13], v[28:29]
	v_mov_b64_e32 v[14:15], v[30:31]
	s_waitcnt lgkmcnt(1)
	v_mfma_f32_32x32x16_bf16 v[32:47], v[122:125], v[156:159], v[32:47]
	s_waitcnt lgkmcnt(0)
	v_mfma_f32_32x32x16_bf16 v[0:15], v[204:207], v[156:159], v[0:15]

	v_mov_b64_e32 v[16:17], v[96:97]
	v_mov_b64_e32 v[18:19], v[98:99]
	v_mov_b64_e32 v[20:21], v[100:101]
	v_mov_b64_e32 v[22:23], v[102:103]
	v_mov_b64_e32 v[24:25], v[104:105]
	v_mov_b64_e32 v[26:27], v[106:107]
	v_mov_b64_e32 v[28:29], v[108:109]
	v_mov_b64_e32 v[30:31], v[110:111]
	s_branch .LBB0_868

.LBB0_881:
	s_add_i32 s0, 0, 0x14000
	v_add_u32_e32 v68, s0, v189
	v_add_u32_e32 v76, s0, v190
	v_add_u32_e32 v84, s0, v191
	v_add_u32_e32 v92, s0, v192
	ds_read_b128 v[64:67], v68
	ds_read_b128 v[68:71], v68 offset:4096
	ds_read_b128 v[72:75], v76
	ds_read_b128 v[76:79], v76 offset:4096
	ds_read_b128 v[80:83], v84
	ds_read_b128 v[84:87], v84 offset:4096
	ds_read_b128 v[88:91], v92
	ds_read_b128 v[92:95], v92 offset:4096

	s_waitcnt lgkmcnt(7)
	v_mfma_f32_32x32x16_bf16 v[16:31], v[64:67], v[144:147], v[16:31]
	s_waitcnt lgkmcnt(6)
	v_mfma_f32_32x32x16_bf16 v[48:63], v[68:71], v[144:147], v[48:63]
	s_waitcnt lgkmcnt(5)
	v_mfma_f32_32x32x16_bf16 v[16:31], v[72:75], v[148:151], v[16:31]
	s_waitcnt lgkmcnt(4)
	v_mfma_f32_32x32x16_bf16 v[48:63], v[76:79], v[148:151], v[48:63]
	s_waitcnt lgkmcnt(3)
	v_mfma_f32_32x32x16_bf16 v[16:31], v[80:83], v[152:155], v[16:31]
	s_waitcnt lgkmcnt(2)
	v_mfma_f32_32x32x16_bf16 v[48:63], v[84:87], v[152:155], v[48:63]
	s_waitcnt lgkmcnt(1)
	v_mfma_f32_32x32x16_bf16 v[16:31], v[88:91], v[156:159], v[16:31]
	s_waitcnt lgkmcnt(0)
	v_mfma_f32_32x32x16_bf16 v[48:63], v[92:95], v[156:159], v[48:63]

	v_readlane_b32 s0, v255, 3
	s_nop 1
	v_add_u32_e32 v68, s0, v189
	v_add_u32_e32 v76, s0, v190
	v_add_u32_e32 v84, s0, v191
	v_add_u32_e32 v92, s0, v192
	ds_read_b128 v[64:67], v68
	ds_read_b128 v[68:71], v68 offset:4096
	ds_read_b128 v[72:75], v76
	ds_read_b128 v[76:79], v76 offset:4096
	ds_read_b128 v[80:83], v84
	ds_read_b128 v[84:87], v84 offset:4096
	ds_read_b128 v[88:91], v92
	ds_read_b128 v[92:95], v92 offset:4096

	s_waitcnt lgkmcnt(7)
	v_mfma_f32_32x32x16_bf16 v[32:47], v[64:67], v[144:147], v[32:47]
	s_waitcnt lgkmcnt(6)
	v_mfma_f32_32x32x16_bf16 v[0:15], v[68:71], v[144:147], v[0:15]
	s_waitcnt lgkmcnt(5)
	v_mfma_f32_32x32x16_bf16 v[32:47], v[72:75], v[148:151], v[32:47]
	s_waitcnt lgkmcnt(4)
	v_mfma_f32_32x32x16_bf16 v[0:15], v[76:79], v[148:151], v[0:15]
	s_waitcnt lgkmcnt(3)
	v_mfma_f32_32x32x16_bf16 v[32:47], v[80:83], v[152:155], v[32:47]
	s_waitcnt lgkmcnt(2)
	v_mfma_f32_32x32x16_bf16 v[0:15], v[84:87], v[152:155], v[0:15]
	s_waitcnt lgkmcnt(1)
	v_mfma_f32_32x32x16_bf16 v[32:47], v[88:91], v[156:159], v[32:47]
	s_waitcnt lgkmcnt(0)
	v_mfma_f32_32x32x16_bf16 v[0:15], v[92:95], v[156:159], v[0:15]


; #define CLASSIFY(kv0_, act_, cls_) do { act_ = true; if (SWA) act_ = ((kv0_) + 63 >= qw - 128) && ((kv0_) <= qw + 159); \
;         cls_ = 0; if ((kv0_) + 63 < qw) cls_ = 1; else if ((kv0_) > qw + 31) cls_ = 2; \
;         if (SWA) { if (cls_ == 1 && qw + 31 - (kv0_) > 128) cls_ = 0; if (cls_ == 2 && (kv0_) + 63 - qw > 128) cls_ = 0; } } while (0)
; template <bool SWA>
; __device__ __forceinline__ void unit(LAS unsigned char* lds, const bf16_t* PROJ, const bf16_t* KT, const bf16_t* VT, bf16_t* OB, int opitch, int ocol, int b, int head, int qb, float slope2, float m_init, float lam, const float* subg) {
;     ...
;         const int kva = TILE_OF(sa) * 64, kvb = TILE_OF(sb < nsteps ? sb : sa) * 64;
;         bool acta, actb; int clsa, clsb;
;         CLASSIFY(kva, acta, clsa); CLASSIFY(kvb, actb, clsb); actb = actb && (sb < nsteps);
.LBB0_887:
	s_add_i32 s28, s1, -4
	s_and_b64 s[6:7], s[78:79], exec
	s_cselect_b32 s6, s27, s28
	s_lshl_b32 s28, s6, 6
	s_or_b32 s6, s28, 63
	s_cmp_ge_i32 s6, s5
	s_cselect_b64 s[86:87], -1, 0
	s_cmp_lt_i32 s6, s5
	s_cselect_b64 s[78:79], -1, 0
	s_cmp_le_i32 s28, s19
	s_cselect_b64 s[88:89], -1, 0
	s_add_i32 s6, s25, 0xffff4000
	s_and_b32 s6, s6, 0x8000
	s_add_i32 s29, s6, 0
	v_add_u32_e32 v65, s29, v199
	ds_read_b128 v[66:69], v65
	ds_read_b128 v[70:73], v65 offset:8192
	v_add_u32_e32 v65, s29, v200
	ds_read_b128 v[74:77], v65
	ds_read_b128 v[78:81], v65 offset:8192
	v_add_u32_e32 v65, s29, v201
	ds_read_b128 v[82:85], v65
	ds_read_b128 v[86:89], v65 offset:8192
	v_add_u32_e32 v65, s29, v202
	ds_read_b128 v[90:93], v65
	ds_read_b128 v[204:207], v65 offset:8192
	s_and_b64 s[80:81], s[86:87], s[88:89]

	s_waitcnt lgkmcnt(7)
	v_mfma_f32_32x32x16_bf16 v[112:127], v[66:69], v[140:143], v[96:111]
	s_waitcnt lgkmcnt(6)
	v_mfma_f32_32x32x16_bf16 v[96:111], v[70:73], v[140:143], v[96:111]
	s_waitcnt lgkmcnt(5)
	v_mfma_f32_32x32x16_bf16 v[112:127], v[74:77], v[136:139], v[112:127]
	s_waitcnt lgkmcnt(4)
	v_mfma_f32_32x32x16_bf16 v[96:111], v[78:81], v[136:139], v[96:111]
	s_waitcnt lgkmcnt(3)
	v_mfma_f32_32x32x16_bf16 v[112:127], v[82:85], v[132:135], v[112:127]
	s_waitcnt lgkmcnt(2)
	v_mfma_f32_32x32x16_bf16 v[96:111], v[86:89], v[132:135], v[96:111]
	s_waitcnt lgkmcnt(1)
	v_mfma_f32_32x32x16_bf16 v[112:127], v[90:93], v[128:131], v[112:127]
	s_waitcnt lgkmcnt(0)
	v_mfma_f32_32x32x16_bf16 v[96:111], v[204:207], v[128:131], v[96:111]

	s_mov_b32 m0, s32
	s_nop 0
	global_load_lds_dwordx4 v164, s[98:99]
	s_add_i32 m0, s32, 0x400
	s_nop 0
	global_load_lds_dwordx4 v170, s[98:99]
	s_and_b64 vcc, exec, s[80:81]
	v_mov_b32_e32 v65, 0
	v_mov_b32_e32 v66, 0
	v_mov_b32_e32 v67, 0
	v_mov_b32_e32 v68, 0
	v_mov_b32_e32 v69, 0
	v_mov_b32_e32 v70, 0
	v_mov_b32_e32 v71, 0
	v_mov_b32_e32 v72, 0
	v_mov_b32_e32 v73, 0
	v_mov_b32_e32 v74, 0
	v_mov_b32_e32 v75, 0
	v_mov_b32_e32 v76, 0
	v_mov_b32_e32 v77, 0
	v_mov_b32_e32 v78, 0
	v_mov_b32_e32 v79, 0
	s_cbranch_vccnz .LBB0_889
	s_and_b64 s[6:7], s[88:89], exec
	s_cselect_b32 s27, 0, 64
	s_and_b64 s[6:7], s[86:87], exec
	s_cselect_b32 s6, s27, 0
	s_add_i32 s6, s6, 0
	s_add_i32 s6, s6, 0x20200
	v_mov_b32_e32 v76, s6
	ds_read_b128 v[64:67], v76
	ds_read_b128 v[68:71], v76 offset:16
	ds_read_b128 v[72:75], v76 offset:32
	ds_read_b128 v[76:79], v76 offset:48
.LBB0_889:
	s_add_i32 s6, s25, 0xffff8000
	s_and_b32 s6, s6, 0xc000
	s_add_i32 s27, s6, 0
	v_add_u32_e32 v80, s27, v199
	ds_read_b128 v[204:207], v80
	ds_read_b128 v[208:211], v80 offset:8192
	v_add_u32_e32 v80, s27, v200
	ds_read_b128 v[212:215], v80
	ds_read_b128 v[216:219], v80 offset:8192
	v_add_u32_e32 v80, s27, v201
	ds_read_b128 v[220:223], v80
	ds_read_b128 v[224:227], v80 offset:8192
	v_add_u32_e32 v80, s27, v202
	ds_read_b128 v[228:231], v80
	ds_read_b128 v[232:235], v80 offset:8192
	s_xor_b64 s[34:35], s[84:85], -1

	s_waitcnt lgkmcnt(7)
	v_mfma_f32_32x32x16_bf16 v[80:95], v[204:207], v[140:143], v[64:79]
	s_waitcnt lgkmcnt(6)
	v_mfma_f32_32x32x16_bf16 v[64:79], v[208:211], v[140:143], v[64:79]
	s_waitcnt lgkmcnt(5)
	v_mfma_f32_32x32x16_bf16 v[80:95], v[212:215], v[136:139], v[80:95]
	s_waitcnt lgkmcnt(4)
	v_mfma_f32_32x32x16_bf16 v[64:79], v[216:219], v[136:139], v[64:79]
	s_waitcnt lgkmcnt(3)
	v_mfma_f32_32x32x16_bf16 v[80:95], v[220:223], v[132:135], v[80:95]
	s_waitcnt lgkmcnt(2)
	v_mfma_f32_32x32x16_bf16 v[64:79], v[224:227], v[132:135], v[64:79]
	s_waitcnt lgkmcnt(1)
	v_mfma_f32_32x32x16_bf16 v[80:95], v[228:231], v[128:131], v[80:95]
	s_waitcnt lgkmcnt(0)
	v_mfma_f32_32x32x16_bf16 v[64:79], v[232:235], v[128:131], v[64:79]

	s_mov_b32 m0, s71
	s_nop 0
	global_load_lds_dwordx4 v168, s[100:101]
	s_add_i32 m0, s71, 0x400
	s_nop 0
	global_load_lds_dwordx4 v172, s[100:101]
	v_or_b32_e32 v174, s30, v187
	v_sub_u32_e32 v174, v188, v174
	v_cvt_f32_i32_e32 v174, v174
	s_mov_b64 s[6:7], -1
	s_and_b64 vcc, exec, s[34:35]
	s_cbranch_vccz .LBB0_895
	s_andn2_b64 vcc, exec, s[82:83]
	s_cbranch_vccnz .LBB0_892
	v_mul_f32_e64 v204, -s76, v174
	v_fma_f32 v205, -s76, v174, v194
	s_mov_b64 s[6:7], 0

.LBB0_902:
	s_add_i32 s29, s29, 0x10000
	v_add_u32_e32 v179, s29, v189
	v_add_u32_e32 v203, s29, v190
	v_add_u32_e32 v204, s29, v191
	v_add_u32_e32 v205, s29, v192
	ds_read_b128 v[96:99], v179
	ds_read_b128 v[100:103], v179 offset:4096
	ds_read_b128 v[104:107], v203
	ds_read_b128 v[108:111], v203 offset:4096
	ds_read_b128 v[112:115], v204
	ds_read_b128 v[116:119], v204 offset:4096
	ds_read_b128 v[120:123], v205
	ds_read_b128 v[124:127], v205 offset:4096

	s_waitcnt lgkmcnt(7)
	v_mfma_f32_32x32x16_bf16 v[16:31], v[96:99], v[144:147], v[16:31]
	s_waitcnt lgkmcnt(6)
	v_mfma_f32_32x32x16_bf16 v[48:63], v[100:103], v[144:147], v[48:63]
	s_waitcnt lgkmcnt(5)
	v_mfma_f32_32x32x16_bf16 v[16:31], v[104:107], v[148:151], v[16:31]
	s_waitcnt lgkmcnt(4)
	v_mfma_f32_32x32x16_bf16 v[48:63], v[108:111], v[148:151], v[48:63]
	s_waitcnt lgkmcnt(3)
	v_mfma_f32_32x32x16_bf16 v[16:31], v[112:115], v[152:155], v[16:31]
	s_waitcnt lgkmcnt(2)
	v_mfma_f32_32x32x16_bf16 v[48:63], v[116:119], v[152:155], v[48:63]
	s_waitcnt lgkmcnt(1)
	v_mfma_f32_32x32x16_bf16 v[16:31], v[120:123], v[156:159], v[16:31]
	s_waitcnt lgkmcnt(0)
	v_mfma_f32_32x32x16_bf16 v[48:63], v[124:127], v[156:159], v[48:63]

	ds_read_b128 v[96:99], v179 offset:8192
	ds_read_b128 v[100:103], v179 offset:12288
	ds_read_b128 v[104:107], v203 offset:8192
	ds_read_b128 v[108:111], v203 offset:12288
	ds_read_b128 v[112:115], v204 offset:8192
	ds_read_b128 v[116:119], v204 offset:12288
	ds_read_b128 v[120:123], v205 offset:8192
	ds_read_b128 v[124:127], v205 offset:12288

	s_waitcnt lgkmcnt(7)
	v_mfma_f32_32x32x16_bf16 v[32:47], v[96:99], v[144:147], v[32:47]
	s_waitcnt lgkmcnt(6)
	v_mfma_f32_32x32x16_bf16 v[0:15], v[100:103], v[144:147], v[0:15]
	s_waitcnt lgkmcnt(5)
	v_mfma_f32_32x32x16_bf16 v[32:47], v[104:107], v[148:151], v[32:47]
	s_waitcnt lgkmcnt(4)
	v_mfma_f32_32x32x16_bf16 v[0:15], v[108:111], v[148:151], v[0:15]
	s_waitcnt lgkmcnt(3)
	v_mfma_f32_32x32x16_bf16 v[32:47], v[112:115], v[152:155], v[32:47]
	s_waitcnt lgkmcnt(2)
	v_mfma_f32_32x32x16_bf16 v[0:15], v[116:119], v[152:155], v[0:15]
	s_waitcnt lgkmcnt(1)
	v_mfma_f32_32x32x16_bf16 v[32:47], v[120:123], v[156:159], v[32:47]
	s_waitcnt lgkmcnt(0)
	v_mfma_f32_32x32x16_bf16 v[0:15], v[124:127], v[156:159], v[0:15]


.LBB0_916:
	s_add_i32 s27, s27, 0x10000
	v_add_u32_e32 v96, s27, v189
	v_add_u32_e32 v97, s27, v190
	v_add_u32_e32 v98, s27, v191
	v_add_u32_e32 v99, s27, v192
	ds_read_b128 v[64:67], v96
	ds_read_b128 v[68:71], v96 offset:4096
	ds_read_b128 v[72:75], v97
	ds_read_b128 v[76:79], v97 offset:4096
	ds_read_b128 v[80:83], v98
	ds_read_b128 v[84:87], v98 offset:4096
	ds_read_b128 v[88:91], v99
	ds_read_b128 v[92:95], v99 offset:4096

	s_waitcnt lgkmcnt(7)
	v_mfma_f32_32x32x16_bf16 v[16:31], v[64:67], v[144:147], v[16:31]
	s_waitcnt lgkmcnt(6)
	v_mfma_f32_32x32x16_bf16 v[48:63], v[68:71], v[144:147], v[48:63]
	s_waitcnt lgkmcnt(5)
	v_mfma_f32_32x32x16_bf16 v[16:31], v[72:75], v[148:151], v[16:31]
	s_waitcnt lgkmcnt(4)
	v_mfma_f32_32x32x16_bf16 v[48:63], v[76:79], v[148:151], v[48:63]
	s_waitcnt lgkmcnt(3)
	v_mfma_f32_32x32x16_bf16 v[16:31], v[80:83], v[152:155], v[16:31]
	s_waitcnt lgkmcnt(2)
	v_mfma_f32_32x32x16_bf16 v[48:63], v[84:87], v[152:155], v[48:63]
	s_waitcnt lgkmcnt(1)
	v_mfma_f32_32x32x16_bf16 v[16:31], v[88:91], v[156:159], v[16:31]
	s_waitcnt lgkmcnt(0)
	v_mfma_f32_32x32x16_bf16 v[48:63], v[92:95], v[156:159], v[48:63]

	ds_read_b128 v[64:67], v96 offset:8192
	ds_read_b128 v[68:71], v96 offset:12288
	ds_read_b128 v[72:75], v97 offset:8192
	ds_read_b128 v[76:79], v97 offset:12288
	ds_read_b128 v[80:83], v98 offset:8192
	ds_read_b128 v[84:87], v98 offset:12288
	ds_read_b128 v[88:91], v99 offset:8192
	ds_read_b128 v[92:95], v99 offset:12288

	s_waitcnt lgkmcnt(7)
	v_mfma_f32_32x32x16_bf16 v[32:47], v[64:67], v[144:147], v[32:47]
	s_waitcnt lgkmcnt(6)
	v_mfma_f32_32x32x16_bf16 v[0:15], v[68:71], v[144:147], v[0:15]
	s_waitcnt lgkmcnt(5)
	v_mfma_f32_32x32x16_bf16 v[32:47], v[72:75], v[148:151], v[32:47]
	s_waitcnt lgkmcnt(4)
	v_mfma_f32_32x32x16_bf16 v[0:15], v[76:79], v[148:151], v[0:15]
	s_waitcnt lgkmcnt(3)
	v_mfma_f32_32x32x16_bf16 v[32:47], v[80:83], v[152:155], v[32:47]
	s_waitcnt lgkmcnt(2)
	v_mfma_f32_32x32x16_bf16 v[0:15], v[84:87], v[152:155], v[0:15]
	s_waitcnt lgkmcnt(1)
	v_mfma_f32_32x32x16_bf16 v[32:47], v[88:91], v[156:159], v[32:47]
	s_waitcnt lgkmcnt(0)
	v_mfma_f32_32x32x16_bf16 v[0:15], v[92:95], v[156:159], v[0:15]

; #define DMA_T(s_) do { DMA_K(s_); DMA_V(s_); } while (0)
; #define WAIT_BAR() do { asm volatile("s_waitcnt vmcnt(0) lgkmcnt(0)" ::: "memory"); __builtin_amdgcn_s_barrier(); asm volatile("" ::: "memory"); } while (0)
; #define CLASSIFY(kv0_, act_, cls_) do { act_ = true; if (SWA) act_ = ((kv0_) + 63 >= qw - 128) && ((kv0_) <= qw + 159); \
;         cls_ = 0; if ((kv0_) + 63 < qw) cls_ = 1; else if ((kv0_) > qw + 31) cls_ = 2; \
;         if (SWA) { if (cls_ == 1 && qw + 31 - (kv0_) > 128) cls_ = 0; if (cls_ == 2 && (kv0_) + 63 - qw > 128) cls_ = 0; } } while (0)
; template <bool SWA>
; __device__ __forceinline__ void unit(LAS unsigned char* lds, const bf16_t* PROJ, const bf16_t* KT, const bf16_t* VT, bf16_t* OB, int opitch, int ocol, int b, int head, int qb, float slope2, float m_init, float lam, const float* subg) {
;     ...
;     for (int S = 0; S < npairs; ++S) {
;         const int sa = 2 * S, sb = 2 * S + 1;
;         if (sa + 2 < nsteps) DMA_T(sa + 2);
;         if (sb + 2 < nsteps) DMA_T(sb + 2);
;         const int kva = TILE_OF(sa) * 64, kvb = TILE_OF(sb < nsteps ? sb : sa) * 64;
;         bool acta, actb; int clsa, clsb;
;         CLASSIFY(kva, acta, clsa); CLASSIFY(kvb, actb, clsb); actb = actb && (sb < nsteps);
;         f32x16 s0, s1, u0, u1;
;         if (acta) QK_T(s0, s1, sa, clsa);
;         if (actb) QK_T(u0, u1, sb, clsb);
;         if (acta) { SM_T(s0, s1, kva, clsa); if (pvalid) PV_TILE(sa); }
;         if (actb) { SM_T(u0, u1, kvb, clsb); if (pvalid) PV_TILE(sb); }
;         WAIT_BAR();
	s_branch .LBB0_883

; #define CLASSIFY(kv0_, act_, cls_) do { act_ = true; if (SWA) act_ = ((kv0_) + 63 >= qw - 128) && ((kv0_) <= qw + 159); \
;         cls_ = 0; if ((kv0_) + 63 < qw) cls_ = 1; else if ((kv0_) > qw + 31) cls_ = 2; \
;         if (SWA) { if (cls_ == 1 && qw + 31 - (kv0_) > 128) cls_ = 0; if (cls_ == 2 && (kv0_) + 63 - qw > 128) cls_ = 0; } } while (0)
; template <bool SWA>
; __device__ __forceinline__ void unit(LAS unsigned char* lds, const bf16_t* PROJ, const bf16_t* KT, const bf16_t* VT, bf16_t* OB, int opitch, int ocol, int b, int head, int qb, float slope2, float m_init, float lam, const float* subg) {
;     ...
;         const int kva = TILE_OF(sa) * 64, kvb = TILE_OF(sb < nsteps ? sb : sa) * 64;
;         bool acta, actb; int clsa, clsb;
;         CLASSIFY(kva, acta, clsa); CLASSIFY(kvb, actb, clsb); actb = actb && (sb < nsteps);
.LBB0_920:
	ds_read_b128 v[66:69], v195 offset:32768
	ds_read_b128 v[70:73], v195 offset:40960
	ds_read_b128 v[74:77], v196 offset:32768
	ds_read_b128 v[78:81], v196 offset:40960
	ds_read_b128 v[82:85], v197 offset:32768
	ds_read_b128 v[86:89], v197 offset:40960
	ds_read_b128 v[90:93], v198 offset:32768
	ds_read_b128 v[168:171], v198 offset:40960
	s_and_b64 s[6:7], s[78:79], exec
	s_movk_i32 s0, 0x740
	s_cselect_b32 s0, s0, 0x7c0
	s_or_b32 s2, s0, 63
	s_cmp_ge_u32 s2, s5
	s_cselect_b64 s[86:87], -1, 0
	s_cmp_lt_u32 s2, s5
	s_cselect_b64 s[78:79], -1, 0
	s_cmp_le_u32 s0, s19
	s_cselect_b64 s[88:89], -1, 0
	s_and_b64 s[80:81], s[86:87], s[88:89]

	s_waitcnt lgkmcnt(7)
	v_mfma_f32_32x32x16_bf16 v[112:127], v[66:69], v[140:143], v[96:111]
	s_waitcnt lgkmcnt(6)
	v_mfma_f32_32x32x16_bf16 v[96:111], v[70:73], v[140:143], v[96:111]
	s_waitcnt lgkmcnt(5)
	v_mfma_f32_32x32x16_bf16 v[112:127], v[74:77], v[136:139], v[112:127]
	s_waitcnt lgkmcnt(4)
	v_mfma_f32_32x32x16_bf16 v[96:111], v[78:81], v[136:139], v[96:111]
	s_waitcnt lgkmcnt(3)
	v_mfma_f32_32x32x16_bf16 v[112:127], v[82:85], v[132:135], v[112:127]
	s_waitcnt lgkmcnt(2)
	v_mfma_f32_32x32x16_bf16 v[96:111], v[86:89], v[132:135], v[96:111]
	s_waitcnt lgkmcnt(1)
	v_mfma_f32_32x32x16_bf16 v[112:127], v[90:93], v[128:131], v[112:127]
	s_waitcnt lgkmcnt(0)
	v_mfma_f32_32x32x16_bf16 v[96:111], v[168:171], v[128:131], v[96:111]

	s_and_b64 vcc, exec, s[80:81]
	v_mov_b32_e32 v65, 0
	v_mov_b32_e32 v66, 0
	v_mov_b32_e32 v67, 0
	v_mov_b32_e32 v68, 0
	v_mov_b32_e32 v69, 0
	v_mov_b32_e32 v70, 0
	v_mov_b32_e32 v71, 0
	v_mov_b32_e32 v72, 0
	v_mov_b32_e32 v73, 0
	v_mov_b32_e32 v74, 0
	v_mov_b32_e32 v75, 0
	v_mov_b32_e32 v76, 0
	v_mov_b32_e32 v77, 0
	v_mov_b32_e32 v78, 0
	v_mov_b32_e32 v79, 0
	s_cbranch_vccnz .LBB0_922
	s_and_b64 s[6:7], s[88:89], exec
	s_cselect_b32 s2, 0, 64
	s_and_b64 s[6:7], s[86:87], exec
	s_cselect_b32 s2, s2, 0
	s_add_i32 s2, s2, 0
	s_add_i32 s2, s2, 0x20200
	v_mov_b32_e32 v76, s2
	ds_read_b128 v[64:67], v76
	ds_read_b128 v[68:71], v76 offset:16
	ds_read_b128 v[72:75], v76 offset:32
	ds_read_b128 v[76:79], v76 offset:48
.LBB0_922:
	ds_read_b128 v[168:171], v195 offset:49152
	ds_read_b128 v[204:207], v195 offset:57344
	ds_read_b128 v[208:211], v196 offset:49152
	ds_read_b128 v[212:215], v196 offset:57344
	ds_read_b128 v[216:219], v197 offset:49152
	ds_read_b128 v[220:223], v197 offset:57344
	ds_read_b128 v[224:227], v198 offset:49152
	ds_read_b128 v[196:199], v198 offset:57344
	s_xor_b64 s[6:7], s[84:85], -1

	s_waitcnt lgkmcnt(7)
	v_mfma_f32_32x32x16_bf16 v[80:95], v[168:171], v[140:143], v[64:79]
	s_waitcnt lgkmcnt(6)
	v_mfma_f32_32x32x16_bf16 v[64:79], v[204:207], v[140:143], v[64:79]
	s_waitcnt lgkmcnt(5)
	v_mfma_f32_32x32x16_bf16 v[80:95], v[208:211], v[136:139], v[80:95]
	s_waitcnt lgkmcnt(4)
	v_mfma_f32_32x32x16_bf16 v[64:79], v[212:215], v[136:139], v[64:79]
	s_waitcnt lgkmcnt(3)
	v_mfma_f32_32x32x16_bf16 v[80:95], v[216:219], v[132:135], v[80:95]
	s_waitcnt lgkmcnt(2)
	v_mfma_f32_32x32x16_bf16 v[64:79], v[220:223], v[132:135], v[64:79]
	s_waitcnt lgkmcnt(1)
	v_mfma_f32_32x32x16_bf16 v[80:95], v[224:227], v[128:131], v[80:95]
	s_waitcnt lgkmcnt(0)
	v_mfma_f32_32x32x16_bf16 v[64:79], v[196:199], v[128:131], v[64:79]

	v_or_b32_e32 v128, s1, v187
	v_sub_u32_e32 v129, v188, v128
	v_cvt_f32_i32_e32 v128, v129
	s_andn2_b64 vcc, exec, s[6:7]
	s_mov_b64 s[6:7], -1
	s_cbranch_vccnz .LBB0_928
	s_andn2_b64 vcc, exec, s[82:83]
	s_cbranch_vccnz .LBB0_925
	v_mul_f32_e64 v130, -s76, v128
	v_fma_f32 v131, -s76, v128, v194
	s_mov_b64 s[6:7], 0

.LBB0_935:
	s_add_i32 s1, 0, 0x18000
	v_add_u32_e32 v100, s1, v189
	v_add_u32_e32 v108, s1, v190
	v_add_u32_e32 v116, s1, v191
	v_add_u32_e32 v124, s1, v192
	ds_read_b128 v[96:99], v100
	ds_read_b128 v[100:103], v100 offset:4096
	ds_read_b128 v[104:107], v108
	ds_read_b128 v[108:111], v108 offset:4096
	ds_read_b128 v[112:115], v116
	ds_read_b128 v[116:119], v116 offset:4096
	ds_read_b128 v[120:123], v124
	ds_read_b128 v[124:127], v124 offset:4096

	s_waitcnt lgkmcnt(7)
	v_mfma_f32_32x32x16_bf16 v[16:31], v[96:99], v[144:147], v[16:31]
	s_waitcnt lgkmcnt(6)
	v_mfma_f32_32x32x16_bf16 v[48:63], v[100:103], v[144:147], v[48:63]
	s_waitcnt lgkmcnt(5)
	v_mfma_f32_32x32x16_bf16 v[16:31], v[104:107], v[148:151], v[16:31]
	s_waitcnt lgkmcnt(4)
	v_mfma_f32_32x32x16_bf16 v[48:63], v[108:111], v[148:151], v[48:63]
	s_waitcnt lgkmcnt(3)
	v_mfma_f32_32x32x16_bf16 v[16:31], v[112:115], v[152:155], v[16:31]
	s_waitcnt lgkmcnt(2)
	v_mfma_f32_32x32x16_bf16 v[48:63], v[116:119], v[152:155], v[48:63]
	s_waitcnt lgkmcnt(1)
	v_mfma_f32_32x32x16_bf16 v[16:31], v[120:123], v[156:159], v[16:31]
	s_waitcnt lgkmcnt(0)
	v_mfma_f32_32x32x16_bf16 v[48:63], v[124:127], v[156:159], v[48:63]

	v_readlane_b32 s1, v255, 4
	s_nop 1
	v_add_u32_e32 v100, s1, v189
	v_add_u32_e32 v108, s1, v190
	v_add_u32_e32 v116, s1, v191
	v_add_u32_e32 v124, s1, v192
	ds_read_b128 v[96:99], v100
	ds_read_b128 v[100:103], v100 offset:4096
	ds_read_b128 v[104:107], v108
	ds_read_b128 v[108:111], v108 offset:4096
	ds_read_b128 v[112:115], v116
	ds_read_b128 v[116:119], v116 offset:4096
	ds_read_b128 v[120:123], v124
	ds_read_b128 v[124:127], v124 offset:4096

	s_waitcnt lgkmcnt(7)
	v_mfma_f32_32x32x16_bf16 v[32:47], v[96:99], v[144:147], v[32:47]
	s_waitcnt lgkmcnt(6)
	v_mfma_f32_32x32x16_bf16 v[0:15], v[100:103], v[144:147], v[0:15]
	s_waitcnt lgkmcnt(5)
	v_mfma_f32_32x32x16_bf16 v[32:47], v[104:107], v[148:151], v[32:47]
	s_waitcnt lgkmcnt(4)
	v_mfma_f32_32x32x16_bf16 v[0:15], v[108:111], v[148:151], v[0:15]
	s_waitcnt lgkmcnt(3)
	v_mfma_f32_32x32x16_bf16 v[32:47], v[112:115], v[152:155], v[32:47]
	s_waitcnt lgkmcnt(2)
	v_mfma_f32_32x32x16_bf16 v[0:15], v[116:119], v[152:155], v[0:15]
	s_waitcnt lgkmcnt(1)
	v_mfma_f32_32x32x16_bf16 v[32:47], v[120:123], v[156:159], v[32:47]
	s_waitcnt lgkmcnt(0)
	v_mfma_f32_32x32x16_bf16 v[0:15], v[124:127], v[156:159], v[0:15]


.LBB0_948:
	s_andn2_b64 vcc, exec, s[76:77]
	s_cbranch_vccnz .LBB0_950
	s_add_i32 s0, 0, 0x1c000
	v_add_u32_e32 v68, s0, v189
	v_add_u32_e32 v76, s0, v190
	v_add_u32_e32 v84, s0, v191
	v_add_u32_e32 v92, s0, v192
	ds_read_b128 v[64:67], v68
	ds_read_b128 v[68:71], v68 offset:4096
	ds_read_b128 v[72:75], v76
	ds_read_b128 v[76:79], v76 offset:4096
	ds_read_b128 v[80:83], v84
	ds_read_b128 v[84:87], v84 offset:4096
	ds_read_b128 v[88:91], v92
	ds_read_b128 v[92:95], v92 offset:4096

	s_waitcnt lgkmcnt(7)
	v_mfma_f32_32x32x16_bf16 v[16:31], v[64:67], v[144:147], v[16:31]
	s_waitcnt lgkmcnt(6)
	v_mfma_f32_32x32x16_bf16 v[48:63], v[68:71], v[144:147], v[48:63]
	s_waitcnt lgkmcnt(5)
	v_mfma_f32_32x32x16_bf16 v[16:31], v[72:75], v[148:151], v[16:31]
	s_waitcnt lgkmcnt(4)
	v_mfma_f32_32x32x16_bf16 v[48:63], v[76:79], v[148:151], v[48:63]
	s_waitcnt lgkmcnt(3)
	v_mfma_f32_32x32x16_bf16 v[16:31], v[80:83], v[152:155], v[16:31]
	s_waitcnt lgkmcnt(2)
	v_mfma_f32_32x32x16_bf16 v[48:63], v[84:87], v[152:155], v[48:63]
	s_waitcnt lgkmcnt(1)
	v_mfma_f32_32x32x16_bf16 v[16:31], v[88:91], v[156:159], v[16:31]
	s_waitcnt lgkmcnt(0)
	v_mfma_f32_32x32x16_bf16 v[48:63], v[92:95], v[156:159], v[48:63]

	v_readlane_b32 s0, v255, 5
	s_nop 1
	v_add_u32_e32 v68, s0, v189
	v_add_u32_e32 v76, s0, v190
	v_add_u32_e32 v84, s0, v191
	v_add_u32_e32 v92, s0, v192
	ds_read_b128 v[64:67], v68
	ds_read_b128 v[68:71], v68 offset:4096
	ds_read_b128 v[72:75], v76
	ds_read_b128 v[76:79], v76 offset:4096
	ds_read_b128 v[80:83], v84
	ds_read_b128 v[84:87], v84 offset:4096
	ds_read_b128 v[88:91], v92
	ds_read_b128 v[92:95], v92 offset:4096

	s_waitcnt lgkmcnt(7)
	v_mfma_f32_32x32x16_bf16 v[32:47], v[64:67], v[144:147], v[32:47]
	s_waitcnt lgkmcnt(6)
	v_mfma_f32_32x32x16_bf16 v[0:15], v[68:71], v[144:147], v[0:15]
	s_waitcnt lgkmcnt(5)
	v_mfma_f32_32x32x16_bf16 v[32:47], v[72:75], v[148:151], v[32:47]
	s_waitcnt lgkmcnt(4)
	v_mfma_f32_32x32x16_bf16 v[0:15], v[76:79], v[148:151], v[0:15]
	s_waitcnt lgkmcnt(3)
	v_mfma_f32_32x32x16_bf16 v[32:47], v[80:83], v[152:155], v[32:47]
	s_waitcnt lgkmcnt(2)
	v_mfma_f32_32x32x16_bf16 v[0:15], v[84:87], v[152:155], v[0:15]
	s_waitcnt lgkmcnt(1)
	v_mfma_f32_32x32x16_bf16 v[32:47], v[88:91], v[156:159], v[32:47]
	s_waitcnt lgkmcnt(0)
	v_mfma_f32_32x32x16_bf16 v[0:15], v[92:95], v[156:159], v[0:15]


.LBB0_973:
	s_and_b32 s7, s80, 0x4000
	s_add_i32 s7, s7, 0
	v_add_u32_e32 v0, s7, v148
	ds_read_b128 v[134:137], v0
	ds_read_b128 v[164:167], v0 offset:4096
	v_add_u32_e32 v0, s7, v150
	ds_read_b128 v[168:171], v0
	ds_read_b128 v[184:187], v0 offset:4096
	v_add_u32_e32 v0, s7, v152
	ds_read_b128 v[188:191], v0
	ds_read_b128 v[192:195], v0 offset:4096
	v_add_u32_e32 v0, s7, v154
	ds_read_b128 v[196:199], v0
	ds_read_b128 v[200:203], v0 offset:4096

	s_waitcnt lgkmcnt(7)
	v_mfma_f32_32x32x16_bf16 v[66:81], v[134:137], v[98:101], v[34:49]
	s_waitcnt lgkmcnt(6)
	v_mfma_f32_32x32x16_bf16 v[34:49], v[164:167], v[98:101], v[34:49]
	s_waitcnt lgkmcnt(5)
	v_mfma_f32_32x32x16_bf16 v[66:81], v[168:171], v[102:105], v[66:81]
	s_waitcnt lgkmcnt(4)
	v_mfma_f32_32x32x16_bf16 v[34:49], v[184:187], v[102:105], v[34:49]
	s_waitcnt lgkmcnt(3)
	v_mfma_f32_32x32x16_bf16 v[66:81], v[188:191], v[106:109], v[66:81]
	s_waitcnt lgkmcnt(2)
	v_mfma_f32_32x32x16_bf16 v[34:49], v[192:195], v[106:109], v[34:49]
	s_waitcnt lgkmcnt(1)
	v_mfma_f32_32x32x16_bf16 v[66:81], v[196:199], v[110:113], v[66:81]
	s_waitcnt lgkmcnt(0)
	v_mfma_f32_32x32x16_bf16 v[34:49], v[200:203], v[110:113], v[34:49]


.LBB0_978:
	s_add_i32 s6, s80, 0x2000
	s_and_b32 s6, s6, 0x6000
	s_add_i32 s6, s6, 0
	v_add_u32_e32 v0, s6, v148
	ds_read_b128 v[134:137], v0
	ds_read_b128 v[164:167], v0 offset:4096
	v_add_u32_e32 v0, s6, v150
	ds_read_b128 v[168:171], v0
	ds_read_b128 v[184:187], v0 offset:4096
	v_add_u32_e32 v0, s6, v152
	ds_read_b128 v[188:191], v0
	ds_read_b128 v[192:195], v0 offset:4096
	v_add_u32_e32 v0, s6, v154
	ds_read_b128 v[196:199], v0
	ds_read_b128 v[200:203], v0 offset:4096

	s_waitcnt lgkmcnt(7)
	v_mfma_f32_32x32x16_bf16 v[82:97], v[134:137], v[98:101], v[50:65]
	s_waitcnt lgkmcnt(6)
	v_mfma_f32_32x32x16_bf16 v[50:65], v[164:167], v[98:101], v[50:65]
	s_waitcnt lgkmcnt(5)
	v_mfma_f32_32x32x16_bf16 v[82:97], v[168:171], v[102:105], v[82:97]
	s_waitcnt lgkmcnt(4)
	v_mfma_f32_32x32x16_bf16 v[50:65], v[184:187], v[102:105], v[50:65]
	s_waitcnt lgkmcnt(3)
	v_mfma_f32_32x32x16_bf16 v[82:97], v[188:191], v[106:109], v[82:97]
	s_waitcnt lgkmcnt(2)
	v_mfma_f32_32x32x16_bf16 v[50:65], v[192:195], v[106:109], v[50:65]
	s_waitcnt lgkmcnt(1)
	v_mfma_f32_32x32x16_bf16 v[82:97], v[196:199], v[110:113], v[82:97]
	s_waitcnt lgkmcnt(0)
	v_mfma_f32_32x32x16_bf16 v[50:65], v[200:203], v[110:113], v[50:65]


.LBB0_994:
	s_and_b32 s6, s80, 0x4000
	s_add_i32 s6, s6, 0
	s_add_i32 s6, s6, 0x10000
	v_add_u32_e32 v0, s6, v149
	v_add_u32_e32 v138, s6, v151
	v_add_u32_e32 v139, s6, v153
	v_add_u32_e32 v162, s6, v155
	ds_read_b128 v[134:137], v0
	ds_read_b128 v[164:167], v0 offset:4096
	ds_read_b128 v[168:171], v138
	ds_read_b128 v[184:187], v138 offset:4096
	ds_read_b128 v[188:191], v139
	ds_read_b128 v[192:195], v139 offset:4096
	ds_read_b128 v[196:199], v162
	ds_read_b128 v[200:203], v162 offset:4096

	s_waitcnt lgkmcnt(7)
	v_mfma_f32_32x32x16_bf16 v[2:17], v[134:137], v[114:117], v[2:17]
	s_waitcnt lgkmcnt(6)
	v_mfma_f32_32x32x16_bf16 v[18:33], v[164:167], v[114:117], v[18:33]
	s_waitcnt lgkmcnt(5)
	v_mfma_f32_32x32x16_bf16 v[2:17], v[168:171], v[118:121], v[2:17]
	s_waitcnt lgkmcnt(4)
	v_mfma_f32_32x32x16_bf16 v[18:33], v[184:187], v[118:121], v[18:33]
	s_waitcnt lgkmcnt(3)
	v_mfma_f32_32x32x16_bf16 v[2:17], v[188:191], v[122:125], v[2:17]
	s_waitcnt lgkmcnt(2)
	v_mfma_f32_32x32x16_bf16 v[18:33], v[192:195], v[122:125], v[18:33]
	s_waitcnt lgkmcnt(1)
	v_mfma_f32_32x32x16_bf16 v[2:17], v[196:199], v[126:129], v[2:17]
	s_waitcnt lgkmcnt(0)
	v_mfma_f32_32x32x16_bf16 v[18:33], v[200:203], v[126:129], v[18:33]


.LBB0_1010:
	s_add_i32 s6, s80, 0x2000
	s_and_b32 s6, s6, 0x6000
	s_add_i32 s6, s6, 0
	s_add_i32 s6, s6, 0x10000
	v_add_u32_e32 v0, s6, v149
	v_add_u32_e32 v138, s6, v151
	v_add_u32_e32 v139, s6, v153
	v_add_u32_e32 v163, s6, v155
	ds_read_b128 v[134:137], v0
	ds_read_b128 v[164:167], v0 offset:4096
	ds_read_b128 v[168:171], v138
	ds_read_b128 v[184:187], v138 offset:4096
	ds_read_b128 v[188:191], v139
	ds_read_b128 v[192:195], v139 offset:4096
	ds_read_b128 v[196:199], v163
	ds_read_b128 v[200:203], v163 offset:4096

	s_waitcnt lgkmcnt(7)
	v_mfma_f32_32x32x16_bf16 v[2:17], v[134:137], v[114:117], v[2:17]
	s_waitcnt lgkmcnt(6)
	v_mfma_f32_32x32x16_bf16 v[18:33], v[164:167], v[114:117], v[18:33]
	s_waitcnt lgkmcnt(5)
	v_mfma_f32_32x32x16_bf16 v[2:17], v[168:171], v[118:121], v[2:17]
	s_waitcnt lgkmcnt(4)
	v_mfma_f32_32x32x16_bf16 v[18:33], v[184:187], v[118:121], v[18:33]
	s_waitcnt lgkmcnt(3)
	v_mfma_f32_32x32x16_bf16 v[2:17], v[188:191], v[122:125], v[2:17]
	s_waitcnt lgkmcnt(2)
	v_mfma_f32_32x32x16_bf16 v[18:33], v[192:195], v[122:125], v[18:33]
	s_waitcnt lgkmcnt(1)
	v_mfma_f32_32x32x16_bf16 v[2:17], v[196:199], v[126:129], v[2:17]
	s_waitcnt lgkmcnt(0)
	v_mfma_f32_32x32x16_bf16 v[18:33], v[200:203], v[126:129], v[18:33]

